# as DAB + D loops: waves 0-3 take the tile barrier before their last 8 P.V MFMAs
# baseline (speedup 1.0000x reference)
; #define SBAR() __builtin_amdgcn_sched_barrier(0)
; template <int D0> __device__ __forceinline__ void pv_one(f32x16& od, int vb, bf16x8 pa0, bf16x8 pa1, bf16x8 pa2, bf16x8 pa3) {
;     const s16x4 l0 = tr_read<v_rd_off(D0, 0, 0)>(vb), h0 = tr_read<v_rd_off(D0, 0, 1)>(vb), l1 = tr_read<v_rd_off(D0, 1, 0)>(vb), h1 = tr_read<v_rd_off(D0, 1, 1)>(vb);
;     const s16x4 l2 = tr_read<v_rd_off(D0, 2, 0)>(vb), h2 = tr_read<v_rd_off(D0, 2, 1)>(vb), l3 = tr_read<v_rd_off(D0, 3, 0)>(vb), h3 = tr_read<v_rd_off(D0, 3, 1)>(vb);
;     asm volatile("s_waitcnt lgkmcnt(0)" ::: "memory"); SBAR();
;     ...
;     od = __builtin_amdgcn_mfma_f32_32x32x16_bf16(pa0, PK(l0, h0), od, 0, 0, 0);
;     od = __builtin_amdgcn_mfma_f32_32x32x16_bf16(pa1, PK(l1, h1), od, 0, 0, 0);
;     od = __builtin_amdgcn_mfma_f32_32x32x16_bf16(pa2, PK(l2, h2), od, 0, 0, 0);
;     od = __builtin_amdgcn_mfma_f32_32x32x16_bf16(pa3, PK(l3, h3), od, 0, 0, 0);
;     ...
; }
; template <bool RSM> __device__ __forceinline__ void pv_d0(f32x16* o, f32x16& lacc, int vb, bf16x8 pa0, bf16x8 pa1, bf16x8 pa2, bf16x8 pa3) {
;     if (RSM) {
;         const bf16x8 ones = {0x3F80, 0x3F80, 0x3F80, 0x3F80, 0x3F80, 0x3F80, 0x3F80, 0x3F80};
;         lacc = __builtin_amdgcn_mfma_f32_32x32x16_bf16(pa0, ones, lacc, 0, 0, 0);
;         lacc = __builtin_amdgcn_mfma_f32_32x32x16_bf16(pa1, ones, lacc, 0, 0, 0);
;         lacc = __builtin_amdgcn_mfma_f32_32x32x16_bf16(pa2, ones, lacc, 0, 0, 0);
;         lacc = __builtin_amdgcn_mfma_f32_32x32x16_bf16(pa3, ones, lacc, 0, 0, 0); }
;     pv_one<0>(o[0], vb, pa0, pa1, pa2, pa3); pv_one<1>(o[1], vb, pa0, pa1, pa2, pa3); pv_one<2>(o[2], vb, pa0, pa1, pa2, pa3); pv_one<3>(o[3], vb, pa0, pa1, pa2, pa3);
; }
.LBB0_704:
	s_mov_b32 s38, s36
	s_mov_b32 s39, s36
	s_mov_b32 s37, s36
	v_mov_b64_e32 v[134:135], s[38:39]
	v_mov_b64_e32 v[132:133], s[36:37]
	s_lshl_b32 s23, s35, 14
	v_add_u32_e32 v0, s23, v230
	v_mfma_f32_32x32x16_bf16 v[96:111], v[6:9], v[132:135], v[96:111]
	ds_read_b64_tr_b16 v[136:137], v0 offset:0
	ds_read_b64_tr_b16 v[138:139], v0 offset:0x800
	ds_read_b64_tr_b16 v[140:141], v0 offset:0x1000
	ds_read_b64_tr_b16 v[142:143], v0 offset:0x1800
	ds_read_b64_tr_b16 v[192:193], v0 offset:0x2000
	ds_read_b64_tr_b16 v[194:195], v0 offset:0x2800
	ds_read_b64_tr_b16 v[196:197], v0 offset:0x3000
	v_mfma_f32_32x32x16_bf16 v[96:111], v[2:5], v[132:135], v[96:111]
	ds_read_b64_tr_b16 v[198:199], v0 offset:0x3800
	s_waitcnt lgkmcnt(0)
	v_mfma_f32_32x32x16_bf16 v[96:111], v[128:131], v[132:135], v[96:111]
	v_mfma_f32_32x32x16_bf16 v[96:111], v[10:13], v[132:135], v[96:111]
	v_mfma_f32_32x32x16_bf16 v[80:95], v[6:9], v[136:139], v[80:95]
	ds_read_b64_tr_b16 v[132:133], v0 offset:0x200
	ds_read_b64_tr_b16 v[134:135], v0 offset:0xa00
	ds_read_b64_tr_b16 v[136:137], v0 offset:0x1200
	ds_read_b64_tr_b16 v[138:139], v0 offset:0x1a00
	v_mfma_f32_32x32x16_bf16 v[80:95], v[2:5], v[140:143], v[80:95]
	ds_read_b64_tr_b16 v[140:141], v0 offset:0x2200
	ds_read_b64_tr_b16 v[142:143], v0 offset:0x2a00
	v_mfma_f32_32x32x16_bf16 v[80:95], v[128:131], v[192:195], v[80:95]
	ds_read_b64_tr_b16 v[192:193], v0 offset:0x3200
	ds_read_b64_tr_b16 v[194:195], v0 offset:0x3a00
	s_waitcnt lgkmcnt(0)
	v_mfma_f32_32x32x16_bf16 v[80:95], v[10:13], v[196:199], v[80:95]
	v_mfma_f32_32x32x16_bf16 v[64:79], v[6:9], v[132:135], v[64:79]
	ds_read_b64_tr_b16 v[132:133], v0 offset:0x400
	ds_read_b64_tr_b16 v[134:135], v0 offset:0xc00
	v_mfma_f32_32x32x16_bf16 v[64:79], v[2:5], v[136:139], v[64:79]
	ds_read_b64_tr_b16 v[136:137], v0 offset:0x1400
	ds_read_b64_tr_b16 v[138:139], v0 offset:0x1c00
	v_mfma_f32_32x32x16_bf16 v[64:79], v[128:131], v[140:143], v[64:79]
	ds_read_b64_tr_b16 v[140:141], v0 offset:0x2400
	ds_read_b64_tr_b16 v[142:143], v0 offset:0x2c00
	v_mfma_f32_32x32x16_bf16 v[64:79], v[10:13], v[192:195], v[64:79]
	ds_read_b64_tr_b16 v[192:193], v0 offset:0x3400
	ds_read_b64_tr_b16 v[194:195], v0 offset:0x3c00
	s_waitcnt lgkmcnt(0)
	s_and_b64 vcc, exec, s[0:1]
	s_cbranch_vccnz .Lmy_slowd8_0
	s_cmpk_gt_u32 s57, 0xfc
	s_cbranch_scc1 .Lmy_slowd8_0
	s_mov_b64 s[20:21], -1
	s_add_i32 m0, s81, s22
	s_addk_i32 s23, 0xc000
	s_cmp_gt_i32 s35, 0
	s_cselect_b32 s20, s23, 0xc000
	s_waitcnt vmcnt(3) lgkmcnt(0)
	s_barrier
	v_mfma_f32_32x32x16_bf16 v[48:63], v[6:9], v[132:135], v[48:63]
	ds_read_b64_tr_b16 v[132:133], v0 offset:0x600
	ds_read_b64_tr_b16 v[134:135], v0 offset:0xe00
	v_mfma_f32_32x32x16_bf16 v[48:63], v[2:5], v[136:139], v[48:63]
	ds_read_b64_tr_b16 v[136:137], v0 offset:0x1600
	ds_read_b64_tr_b16 v[138:139], v0 offset:0x1e00
	v_mfma_f32_32x32x16_bf16 v[48:63], v[128:131], v[140:143], v[48:63]
	ds_read_b64_tr_b16 v[140:141], v0 offset:0x2600
	ds_read_b64_tr_b16 v[142:143], v0 offset:0x2e00
	v_mfma_f32_32x32x16_bf16 v[48:63], v[10:13], v[192:195], v[48:63]
	ds_read_b64_tr_b16 v[192:193], v0 offset:0x3600
	ds_read_b64_tr_b16 v[194:195], v0 offset:0x3e00
	s_waitcnt lgkmcnt(0)
	v_mfma_f32_32x32x16_bf16 v[32:47], v[6:9], v[132:135], v[32:47]
	s_and_b64 vcc, exec, s[0:1]
	v_mfma_f32_32x32x16_bf16 v[32:47], v[2:5], v[136:139], v[32:47]
	v_mfma_f32_32x32x16_bf16 v[32:47], v[128:131], v[140:143], v[32:47]
	v_mfma_f32_32x32x16_bf16 v[32:47], v[10:13], v[192:195], v[32:47]
	s_add_i32 s20, s63, s20
	global_load_lds_dwordx4 v[214:215], off
	s_mov_b32 m0, s20
	v_lshl_add_u64 v[214:215], v[214:215], 0, s[74:75]
	global_load_lds_dwordx4 v[212:213], off
	s_add_i32 m0, s20, 0x2000
	v_lshl_add_u64 v[2:3], v[212:213], 0, s[74:75]
	global_load_lds_dwordx4 v[216:217], off
	v_lshl_add_u64 v[4:5], v[216:217], 0, s[74:75]
	v_mov_b64_e32 v[216:217], v[4:5]
	v_mov_b64_e32 v[212:213], v[2:3]
	s_branch .LBB0_709
.Lmy_slowd8_0:
	v_mfma_f32_32x32x16_bf16 v[48:63], v[6:9], v[132:135], v[48:63]
	ds_read_b64_tr_b16 v[132:133], v0 offset:0x600
	ds_read_b64_tr_b16 v[134:135], v0 offset:0xe00
	v_mfma_f32_32x32x16_bf16 v[48:63], v[2:5], v[136:139], v[48:63]
	ds_read_b64_tr_b16 v[136:137], v0 offset:0x1600
	ds_read_b64_tr_b16 v[138:139], v0 offset:0x1e00
	v_mfma_f32_32x32x16_bf16 v[48:63], v[128:131], v[140:143], v[48:63]
	ds_read_b64_tr_b16 v[140:141], v0 offset:0x2600
	ds_read_b64_tr_b16 v[142:143], v0 offset:0x2e00
	v_mfma_f32_32x32x16_bf16 v[48:63], v[10:13], v[192:195], v[48:63]
	ds_read_b64_tr_b16 v[192:193], v0 offset:0x3600
	ds_read_b64_tr_b16 v[194:195], v0 offset:0x3e00
	s_waitcnt lgkmcnt(0)
	v_mfma_f32_32x32x16_bf16 v[32:47], v[6:9], v[132:135], v[32:47]
	s_and_b64 vcc, exec, s[0:1]
	v_mfma_f32_32x32x16_bf16 v[32:47], v[2:5], v[136:139], v[32:47]
	v_mfma_f32_32x32x16_bf16 v[32:47], v[128:131], v[140:143], v[32:47]
	v_mfma_f32_32x32x16_bf16 v[32:47], v[10:13], v[192:195], v[32:47]
	s_cbranch_vccnz .LBB0_709

; #define SBAR() __builtin_amdgcn_sched_barrier(0)
; template <int D0> __device__ __forceinline__ void pv_one(f32x16& od, int vb, bf16x8 pa0, bf16x8 pa1, bf16x8 pa2, bf16x8 pa3) {
;     const s16x4 l0 = tr_read<v_rd_off(D0, 0, 0)>(vb), h0 = tr_read<v_rd_off(D0, 0, 1)>(vb), l1 = tr_read<v_rd_off(D0, 1, 0)>(vb), h1 = tr_read<v_rd_off(D0, 1, 1)>(vb);
;     const s16x4 l2 = tr_read<v_rd_off(D0, 2, 0)>(vb), h2 = tr_read<v_rd_off(D0, 2, 1)>(vb), l3 = tr_read<v_rd_off(D0, 3, 0)>(vb), h3 = tr_read<v_rd_off(D0, 3, 1)>(vb);
;     asm volatile("s_waitcnt lgkmcnt(0)" ::: "memory"); SBAR();
;     ...
;     od = __builtin_amdgcn_mfma_f32_32x32x16_bf16(pa0, PK(l0, h0), od, 0, 0, 0);
;     od = __builtin_amdgcn_mfma_f32_32x32x16_bf16(pa1, PK(l1, h1), od, 0, 0, 0);
;     od = __builtin_amdgcn_mfma_f32_32x32x16_bf16(pa2, PK(l2, h2), od, 0, 0, 0);
;     od = __builtin_amdgcn_mfma_f32_32x32x16_bf16(pa3, PK(l3, h3), od, 0, 0, 0);
;     ...
; }
; template <bool RSM> __device__ __forceinline__ void pv_d0(f32x16* o, f32x16& lacc, int vb, bf16x8 pa0, bf16x8 pa1, bf16x8 pa2, bf16x8 pa3) {
;     if (RSM) {
;         const bf16x8 ones = {0x3F80, 0x3F80, 0x3F80, 0x3F80, 0x3F80, 0x3F80, 0x3F80, 0x3F80};
;         lacc = __builtin_amdgcn_mfma_f32_32x32x16_bf16(pa0, ones, lacc, 0, 0, 0);
;         lacc = __builtin_amdgcn_mfma_f32_32x32x16_bf16(pa1, ones, lacc, 0, 0, 0);
;         lacc = __builtin_amdgcn_mfma_f32_32x32x16_bf16(pa2, ones, lacc, 0, 0, 0);
;         lacc = __builtin_amdgcn_mfma_f32_32x32x16_bf16(pa3, ones, lacc, 0, 0, 0); }
;     pv_one<0>(o[0], vb, pa0, pa1, pa2, pa3); pv_one<1>(o[1], vb, pa0, pa1, pa2, pa3); pv_one<2>(o[2], vb, pa0, pa1, pa2, pa3); pv_one<3>(o[3], vb, pa0, pa1, pa2, pa3);
; }
.LBB0_719:
	s_mov_b32 s38, s36
	s_mov_b32 s39, s36
	s_mov_b32 s37, s36
	v_mov_b64_e32 v[150:151], s[38:39]
	v_mov_b64_e32 v[148:149], s[36:37]
	s_lshl_b32 s37, s35, 14
	v_add_u32_e32 v14, s37, v230
	v_mfma_f32_32x32x16_bf16 v[96:111], v[6:9], v[148:151], v[96:111]
	ds_read_b64_tr_b16 v[152:153], v14 offset:0
	ds_read_b64_tr_b16 v[154:155], v14 offset:0x800
	ds_read_b64_tr_b16 v[156:157], v14 offset:0x1000
	ds_read_b64_tr_b16 v[158:159], v14 offset:0x1800
	ds_read_b64_tr_b16 v[192:193], v14 offset:0x2000
	ds_read_b64_tr_b16 v[194:195], v14 offset:0x2800
	ds_read_b64_tr_b16 v[196:197], v14 offset:0x3000
	v_mfma_f32_32x32x16_bf16 v[96:111], v[2:5], v[148:151], v[96:111]
	ds_read_b64_tr_b16 v[198:199], v14 offset:0x3800
	s_waitcnt lgkmcnt(0)
	v_mfma_f32_32x32x16_bf16 v[96:111], v[144:147], v[148:151], v[96:111]
	v_mfma_f32_32x32x16_bf16 v[96:111], v[10:13], v[148:151], v[96:111]
	v_mfma_f32_32x32x16_bf16 v[80:95], v[6:9], v[152:155], v[80:95]
	ds_read_b64_tr_b16 v[148:149], v14 offset:0x200
	ds_read_b64_tr_b16 v[150:151], v14 offset:0xa00
	ds_read_b64_tr_b16 v[152:153], v14 offset:0x1200
	ds_read_b64_tr_b16 v[154:155], v14 offset:0x1a00
	v_mfma_f32_32x32x16_bf16 v[80:95], v[2:5], v[156:159], v[80:95]
	ds_read_b64_tr_b16 v[156:157], v14 offset:0x2200
	ds_read_b64_tr_b16 v[158:159], v14 offset:0x2a00
	v_mfma_f32_32x32x16_bf16 v[80:95], v[144:147], v[192:195], v[80:95]
	ds_read_b64_tr_b16 v[192:193], v14 offset:0x3200
	ds_read_b64_tr_b16 v[194:195], v14 offset:0x3a00
	s_waitcnt lgkmcnt(0)
	v_mfma_f32_32x32x16_bf16 v[80:95], v[10:13], v[196:199], v[80:95]
	v_mfma_f32_32x32x16_bf16 v[64:79], v[6:9], v[148:151], v[64:79]
	ds_read_b64_tr_b16 v[148:149], v14 offset:0x400
	ds_read_b64_tr_b16 v[150:151], v14 offset:0xc00
	v_mfma_f32_32x32x16_bf16 v[64:79], v[2:5], v[152:155], v[64:79]
	ds_read_b64_tr_b16 v[152:153], v14 offset:0x1400
	ds_read_b64_tr_b16 v[154:155], v14 offset:0x1c00
	v_mfma_f32_32x32x16_bf16 v[64:79], v[144:147], v[156:159], v[64:79]
	ds_read_b64_tr_b16 v[156:157], v14 offset:0x2400
	ds_read_b64_tr_b16 v[158:159], v14 offset:0x2c00
	v_mfma_f32_32x32x16_bf16 v[64:79], v[10:13], v[192:195], v[64:79]
	ds_read_b64_tr_b16 v[192:193], v14 offset:0x3400
	ds_read_b64_tr_b16 v[194:195], v14 offset:0x3c00
	s_waitcnt lgkmcnt(0)
	s_and_b64 vcc, exec, s[0:1]
	s_cbranch_vccnz .Lmy_slowd8_1
	s_cmpk_gt_u32 s57, 0xfb
	s_cbranch_scc1 .Lmy_slowd8_1
	s_mov_b64 s[22:23], -1
	s_add_i32 m0, s81, s78
	s_addk_i32 s37, 0xc000
	s_cmp_gt_i32 s35, 0
	s_cselect_b32 s22, s37, 0xc000
	s_waitcnt vmcnt(3) lgkmcnt(0)
	s_barrier
	v_mfma_f32_32x32x16_bf16 v[48:63], v[6:9], v[148:151], v[48:63]
	ds_read_b64_tr_b16 v[148:149], v14 offset:0x600
	ds_read_b64_tr_b16 v[150:151], v14 offset:0xe00
	v_mfma_f32_32x32x16_bf16 v[48:63], v[2:5], v[152:155], v[48:63]
	ds_read_b64_tr_b16 v[152:153], v14 offset:0x1600
	ds_read_b64_tr_b16 v[154:155], v14 offset:0x1e00
	v_mfma_f32_32x32x16_bf16 v[48:63], v[144:147], v[156:159], v[48:63]
	ds_read_b64_tr_b16 v[156:157], v14 offset:0x2600
	ds_read_b64_tr_b16 v[158:159], v14 offset:0x2e00
	v_mfma_f32_32x32x16_bf16 v[48:63], v[10:13], v[192:195], v[48:63]
	ds_read_b64_tr_b16 v[192:193], v14 offset:0x3600
	ds_read_b64_tr_b16 v[194:195], v14 offset:0x3e00
	s_waitcnt lgkmcnt(0)
	v_mfma_f32_32x32x16_bf16 v[32:47], v[6:9], v[148:151], v[32:47]
	s_and_b64 vcc, exec, s[0:1]
	v_mfma_f32_32x32x16_bf16 v[32:47], v[2:5], v[152:155], v[32:47]
	v_mfma_f32_32x32x16_bf16 v[32:47], v[144:147], v[156:159], v[32:47]
	v_mfma_f32_32x32x16_bf16 v[32:47], v[10:13], v[192:195], v[32:47]
	s_add_i32 s22, s63, s22
	global_load_lds_dwordx4 v[214:215], off
	s_mov_b32 m0, s22
	v_lshl_add_u64 v[214:215], v[214:215], 0, s[74:75]
	global_load_lds_dwordx4 v[212:213], off
	s_add_i32 m0, s22, 0x2000
	v_lshl_add_u64 v[2:3], v[212:213], 0, s[74:75]
	global_load_lds_dwordx4 v[216:217], off
	v_lshl_add_u64 v[4:5], v[216:217], 0, s[74:75]
	v_mov_b64_e32 v[216:217], v[4:5]
	v_mov_b64_e32 v[212:213], v[2:3]
	s_branch .LBB0_724
.Lmy_slowd8_1:
	v_mfma_f32_32x32x16_bf16 v[48:63], v[6:9], v[148:151], v[48:63]
	ds_read_b64_tr_b16 v[148:149], v14 offset:0x600
	ds_read_b64_tr_b16 v[150:151], v14 offset:0xe00
	v_mfma_f32_32x32x16_bf16 v[48:63], v[2:5], v[152:155], v[48:63]
	ds_read_b64_tr_b16 v[152:153], v14 offset:0x1600
	ds_read_b64_tr_b16 v[154:155], v14 offset:0x1e00
	v_mfma_f32_32x32x16_bf16 v[48:63], v[144:147], v[156:159], v[48:63]
	ds_read_b64_tr_b16 v[156:157], v14 offset:0x2600
	ds_read_b64_tr_b16 v[158:159], v14 offset:0x2e00
	v_mfma_f32_32x32x16_bf16 v[48:63], v[10:13], v[192:195], v[48:63]
	ds_read_b64_tr_b16 v[192:193], v14 offset:0x3600
	ds_read_b64_tr_b16 v[194:195], v14 offset:0x3e00
	s_waitcnt lgkmcnt(0)
	v_mfma_f32_32x32x16_bf16 v[32:47], v[6:9], v[148:151], v[32:47]
	s_and_b64 vcc, exec, s[0:1]
	v_mfma_f32_32x32x16_bf16 v[32:47], v[2:5], v[152:155], v[32:47]
	v_mfma_f32_32x32x16_bf16 v[32:47], v[144:147], v[156:159], v[32:47]
	v_mfma_f32_32x32x16_bf16 v[32:47], v[10:13], v[192:195], v[32:47]
	s_cbranch_vccnz .LBB0_724

; #define SBAR() __builtin_amdgcn_sched_barrier(0)
; template <int D0> __device__ __forceinline__ void pv_one(f32x16& od, int vb, bf16x8 pa0, bf16x8 pa1, bf16x8 pa2, bf16x8 pa3) {
;     const s16x4 l0 = tr_read<v_rd_off(D0, 0, 0)>(vb), h0 = tr_read<v_rd_off(D0, 0, 1)>(vb), l1 = tr_read<v_rd_off(D0, 1, 0)>(vb), h1 = tr_read<v_rd_off(D0, 1, 1)>(vb);
;     const s16x4 l2 = tr_read<v_rd_off(D0, 2, 0)>(vb), h2 = tr_read<v_rd_off(D0, 2, 1)>(vb), l3 = tr_read<v_rd_off(D0, 3, 0)>(vb), h3 = tr_read<v_rd_off(D0, 3, 1)>(vb);
;     asm volatile("s_waitcnt lgkmcnt(0)" ::: "memory"); SBAR();
;     ...
;     od = __builtin_amdgcn_mfma_f32_32x32x16_bf16(pa0, PK(l0, h0), od, 0, 0, 0);
;     od = __builtin_amdgcn_mfma_f32_32x32x16_bf16(pa1, PK(l1, h1), od, 0, 0, 0);
;     od = __builtin_amdgcn_mfma_f32_32x32x16_bf16(pa2, PK(l2, h2), od, 0, 0, 0);
;     od = __builtin_amdgcn_mfma_f32_32x32x16_bf16(pa3, PK(l3, h3), od, 0, 0, 0);
;     ...
; }
; template <bool RSM> __device__ __forceinline__ void pv_d0(f32x16* o, f32x16& lacc, int vb, bf16x8 pa0, bf16x8 pa1, bf16x8 pa2, bf16x8 pa3) {
;     if (RSM) {
;         const bf16x8 ones = {0x3F80, 0x3F80, 0x3F80, 0x3F80, 0x3F80, 0x3F80, 0x3F80, 0x3F80};
;         lacc = __builtin_amdgcn_mfma_f32_32x32x16_bf16(pa0, ones, lacc, 0, 0, 0);
;         lacc = __builtin_amdgcn_mfma_f32_32x32x16_bf16(pa1, ones, lacc, 0, 0, 0);
;         lacc = __builtin_amdgcn_mfma_f32_32x32x16_bf16(pa2, ones, lacc, 0, 0, 0);
;         lacc = __builtin_amdgcn_mfma_f32_32x32x16_bf16(pa3, ones, lacc, 0, 0, 0); }
;     pv_one<0>(o[0], vb, pa0, pa1, pa2, pa3); pv_one<1>(o[1], vb, pa0, pa1, pa2, pa3); pv_one<2>(o[2], vb, pa0, pa1, pa2, pa3); pv_one<3>(o[3], vb, pa0, pa1, pa2, pa3);
; }
.LBB0_779:
	s_mov_b32 s38, s36
	s_mov_b32 s39, s36
	s_mov_b32 s37, s36
	v_mov_b64_e32 v[118:119], s[38:39]
	v_mov_b64_e32 v[116:117], s[36:37]
	s_lshl_b32 s15, s18, 14
	v_add_u32_e32 v0, s15, v192
	v_mfma_f32_32x32x16_bf16 v[80:95], v[6:9], v[116:119], v[80:95]
	ds_read_b64_tr_b16 v[120:121], v0 offset:0
	ds_read_b64_tr_b16 v[122:123], v0 offset:0x800
	ds_read_b64_tr_b16 v[124:125], v0 offset:0x1000
	ds_read_b64_tr_b16 v[126:127], v0 offset:0x1800
	ds_read_b64_tr_b16 v[176:177], v0 offset:0x2000
	ds_read_b64_tr_b16 v[178:179], v0 offset:0x2800
	ds_read_b64_tr_b16 v[180:181], v0 offset:0x3000
	v_mfma_f32_32x32x16_bf16 v[80:95], v[2:5], v[116:119], v[80:95]
	ds_read_b64_tr_b16 v[182:183], v0 offset:0x3800
	s_waitcnt lgkmcnt(0)
	v_mfma_f32_32x32x16_bf16 v[80:95], v[112:115], v[116:119], v[80:95]
	v_mfma_f32_32x32x16_bf16 v[80:95], v[10:13], v[116:119], v[80:95]
	v_mfma_f32_32x32x16_bf16 v[64:79], v[6:9], v[120:123], v[64:79]
	ds_read_b64_tr_b16 v[116:117], v0 offset:0x200
	ds_read_b64_tr_b16 v[118:119], v0 offset:0xa00
	ds_read_b64_tr_b16 v[120:121], v0 offset:0x1200
	ds_read_b64_tr_b16 v[122:123], v0 offset:0x1a00
	v_mfma_f32_32x32x16_bf16 v[64:79], v[2:5], v[124:127], v[64:79]
	ds_read_b64_tr_b16 v[124:125], v0 offset:0x2200
	ds_read_b64_tr_b16 v[126:127], v0 offset:0x2a00
	v_mfma_f32_32x32x16_bf16 v[64:79], v[112:115], v[176:179], v[64:79]
	ds_read_b64_tr_b16 v[176:177], v0 offset:0x3200
	ds_read_b64_tr_b16 v[178:179], v0 offset:0x3a00
	s_waitcnt lgkmcnt(0)
	v_mfma_f32_32x32x16_bf16 v[64:79], v[10:13], v[180:183], v[64:79]
	v_mfma_f32_32x32x16_bf16 v[48:63], v[6:9], v[116:119], v[48:63]
	ds_read_b64_tr_b16 v[116:117], v0 offset:0x400
	ds_read_b64_tr_b16 v[118:119], v0 offset:0xc00
	v_mfma_f32_32x32x16_bf16 v[48:63], v[2:5], v[120:123], v[48:63]
	ds_read_b64_tr_b16 v[120:121], v0 offset:0x1400
	ds_read_b64_tr_b16 v[122:123], v0 offset:0x1c00
	v_mfma_f32_32x32x16_bf16 v[48:63], v[112:115], v[124:127], v[48:63]
	ds_read_b64_tr_b16 v[124:125], v0 offset:0x2400
	ds_read_b64_tr_b16 v[126:127], v0 offset:0x2c00
	v_mfma_f32_32x32x16_bf16 v[48:63], v[10:13], v[176:179], v[48:63]
	ds_read_b64_tr_b16 v[176:177], v0 offset:0x3400
	ds_read_b64_tr_b16 v[178:179], v0 offset:0x3c00
	s_waitcnt lgkmcnt(0)
	s_and_b64 vcc, exec, s[0:1]
	s_cbranch_vccnz .Lmy_slowd8_2
	s_cmpk_gt_u32 s17, 0xfc
	s_cbranch_scc1 .Lmy_slowd8_2
	s_mov_b64 s[12:13], -1
	s_add_i32 m0, s81, s14
	s_addk_i32 s15, 0xc000
	s_cmp_gt_i32 s18, 0
	s_cselect_b32 s12, s15, 0xc000
	s_waitcnt vmcnt(3) lgkmcnt(0)
	s_barrier
	v_mfma_f32_32x32x16_bf16 v[32:47], v[6:9], v[116:119], v[32:47]
	ds_read_b64_tr_b16 v[116:117], v0 offset:0x600
	ds_read_b64_tr_b16 v[118:119], v0 offset:0xe00
	v_mfma_f32_32x32x16_bf16 v[32:47], v[2:5], v[120:123], v[32:47]
	ds_read_b64_tr_b16 v[120:121], v0 offset:0x1600
	ds_read_b64_tr_b16 v[122:123], v0 offset:0x1e00
	v_mfma_f32_32x32x16_bf16 v[32:47], v[112:115], v[124:127], v[32:47]
	ds_read_b64_tr_b16 v[124:125], v0 offset:0x2600
	ds_read_b64_tr_b16 v[126:127], v0 offset:0x2e00
	v_mfma_f32_32x32x16_bf16 v[32:47], v[10:13], v[176:179], v[32:47]
	ds_read_b64_tr_b16 v[176:177], v0 offset:0x3600
	ds_read_b64_tr_b16 v[178:179], v0 offset:0x3e00
	s_waitcnt lgkmcnt(0)
	v_mfma_f32_32x32x16_bf16 v[16:31], v[6:9], v[116:119], v[16:31]
	s_and_b64 vcc, exec, s[0:1]
	v_mfma_f32_32x32x16_bf16 v[16:31], v[2:5], v[120:123], v[16:31]
	v_mfma_f32_32x32x16_bf16 v[16:31], v[112:115], v[124:127], v[16:31]
	v_mfma_f32_32x32x16_bf16 v[16:31], v[10:13], v[176:179], v[16:31]
	s_add_i32 s12, s63, s12
	global_load_lds_dwordx4 v[184:185], off
	s_mov_b32 m0, s12
	v_lshl_add_u64 v[184:185], v[184:185], 0, s[74:75]
	global_load_lds_dwordx4 v[186:187], off
	s_add_i32 m0, s12, 0x2000
	v_lshl_add_u64 v[2:3], v[186:187], 0, s[74:75]
	global_load_lds_dwordx4 v[188:189], off
	v_lshl_add_u64 v[4:5], v[188:189], 0, s[74:75]
	v_mov_b64_e32 v[188:189], v[4:5]
	v_mov_b64_e32 v[186:187], v[2:3]
	s_branch .LBB0_784
.Lmy_slowd8_2:
	v_mfma_f32_32x32x16_bf16 v[32:47], v[6:9], v[116:119], v[32:47]
	ds_read_b64_tr_b16 v[116:117], v0 offset:0x600
	ds_read_b64_tr_b16 v[118:119], v0 offset:0xe00
	v_mfma_f32_32x32x16_bf16 v[32:47], v[2:5], v[120:123], v[32:47]
	ds_read_b64_tr_b16 v[120:121], v0 offset:0x1600
	ds_read_b64_tr_b16 v[122:123], v0 offset:0x1e00
	v_mfma_f32_32x32x16_bf16 v[32:47], v[112:115], v[124:127], v[32:47]
	ds_read_b64_tr_b16 v[124:125], v0 offset:0x2600
	ds_read_b64_tr_b16 v[126:127], v0 offset:0x2e00
	v_mfma_f32_32x32x16_bf16 v[32:47], v[10:13], v[176:179], v[32:47]
	ds_read_b64_tr_b16 v[176:177], v0 offset:0x3600
	ds_read_b64_tr_b16 v[178:179], v0 offset:0x3e00
	s_waitcnt lgkmcnt(0)
	v_mfma_f32_32x32x16_bf16 v[16:31], v[6:9], v[116:119], v[16:31]
	s_and_b64 vcc, exec, s[0:1]
	v_mfma_f32_32x32x16_bf16 v[16:31], v[2:5], v[120:123], v[16:31]
	v_mfma_f32_32x32x16_bf16 v[16:31], v[112:115], v[124:127], v[16:31]
	v_mfma_f32_32x32x16_bf16 v[16:31], v[10:13], v[176:179], v[16:31]
	s_cbranch_vccnz .LBB0_784

; #define SBAR() __builtin_amdgcn_sched_barrier(0)
; template <int D0> __device__ __forceinline__ void pv_one(f32x16& od, int vb, bf16x8 pa0, bf16x8 pa1, bf16x8 pa2, bf16x8 pa3) {
;     const s16x4 l0 = tr_read<v_rd_off(D0, 0, 0)>(vb), h0 = tr_read<v_rd_off(D0, 0, 1)>(vb), l1 = tr_read<v_rd_off(D0, 1, 0)>(vb), h1 = tr_read<v_rd_off(D0, 1, 1)>(vb);
;     const s16x4 l2 = tr_read<v_rd_off(D0, 2, 0)>(vb), h2 = tr_read<v_rd_off(D0, 2, 1)>(vb), l3 = tr_read<v_rd_off(D0, 3, 0)>(vb), h3 = tr_read<v_rd_off(D0, 3, 1)>(vb);
;     asm volatile("s_waitcnt lgkmcnt(0)" ::: "memory"); SBAR();
;     ...
;     od = __builtin_amdgcn_mfma_f32_32x32x16_bf16(pa0, PK(l0, h0), od, 0, 0, 0);
;     od = __builtin_amdgcn_mfma_f32_32x32x16_bf16(pa1, PK(l1, h1), od, 0, 0, 0);
;     od = __builtin_amdgcn_mfma_f32_32x32x16_bf16(pa2, PK(l2, h2), od, 0, 0, 0);
;     od = __builtin_amdgcn_mfma_f32_32x32x16_bf16(pa3, PK(l3, h3), od, 0, 0, 0);
;     ...
; }
; template <bool RSM> __device__ __forceinline__ void pv_d0(f32x16* o, f32x16& lacc, int vb, bf16x8 pa0, bf16x8 pa1, bf16x8 pa2, bf16x8 pa3) {
;     if (RSM) {
;         const bf16x8 ones = {0x3F80, 0x3F80, 0x3F80, 0x3F80, 0x3F80, 0x3F80, 0x3F80, 0x3F80};
;         lacc = __builtin_amdgcn_mfma_f32_32x32x16_bf16(pa0, ones, lacc, 0, 0, 0);
;         lacc = __builtin_amdgcn_mfma_f32_32x32x16_bf16(pa1, ones, lacc, 0, 0, 0);
;         lacc = __builtin_amdgcn_mfma_f32_32x32x16_bf16(pa2, ones, lacc, 0, 0, 0);
;         lacc = __builtin_amdgcn_mfma_f32_32x32x16_bf16(pa3, ones, lacc, 0, 0, 0); }
;     pv_one<0>(o[0], vb, pa0, pa1, pa2, pa3); pv_one<1>(o[1], vb, pa0, pa1, pa2, pa3); pv_one<2>(o[2], vb, pa0, pa1, pa2, pa3); pv_one<3>(o[3], vb, pa0, pa1, pa2, pa3);
; }
.LBB0_794:
	s_mov_b32 s38, s36
	s_mov_b32 s39, s36
	s_mov_b32 s37, s36
	v_mov_b64_e32 v[134:135], s[38:39]
	v_mov_b64_e32 v[132:133], s[36:37]
	s_lshl_b32 s31, s18, 14
	v_add_u32_e32 v14, s31, v192
	v_mfma_f32_32x32x16_bf16 v[80:95], v[6:9], v[132:135], v[80:95]
	ds_read_b64_tr_b16 v[136:137], v14 offset:0
	ds_read_b64_tr_b16 v[138:139], v14 offset:0x800
	ds_read_b64_tr_b16 v[140:141], v14 offset:0x1000
	ds_read_b64_tr_b16 v[142:143], v14 offset:0x1800
	ds_read_b64_tr_b16 v[176:177], v14 offset:0x2000
	ds_read_b64_tr_b16 v[178:179], v14 offset:0x2800
	ds_read_b64_tr_b16 v[180:181], v14 offset:0x3000
	v_mfma_f32_32x32x16_bf16 v[80:95], v[2:5], v[132:135], v[80:95]
	ds_read_b64_tr_b16 v[182:183], v14 offset:0x3800
	s_waitcnt lgkmcnt(0)
	v_mfma_f32_32x32x16_bf16 v[80:95], v[128:131], v[132:135], v[80:95]
	v_mfma_f32_32x32x16_bf16 v[80:95], v[10:13], v[132:135], v[80:95]
	v_mfma_f32_32x32x16_bf16 v[64:79], v[6:9], v[136:139], v[64:79]
	ds_read_b64_tr_b16 v[132:133], v14 offset:0x200
	ds_read_b64_tr_b16 v[134:135], v14 offset:0xa00
	ds_read_b64_tr_b16 v[136:137], v14 offset:0x1200
	ds_read_b64_tr_b16 v[138:139], v14 offset:0x1a00
	v_mfma_f32_32x32x16_bf16 v[64:79], v[2:5], v[140:143], v[64:79]
	ds_read_b64_tr_b16 v[140:141], v14 offset:0x2200
	ds_read_b64_tr_b16 v[142:143], v14 offset:0x2a00
	v_mfma_f32_32x32x16_bf16 v[64:79], v[128:131], v[176:179], v[64:79]
	ds_read_b64_tr_b16 v[176:177], v14 offset:0x3200
	ds_read_b64_tr_b16 v[178:179], v14 offset:0x3a00
	s_waitcnt lgkmcnt(0)
	v_mfma_f32_32x32x16_bf16 v[64:79], v[10:13], v[180:183], v[64:79]
	v_mfma_f32_32x32x16_bf16 v[48:63], v[6:9], v[132:135], v[48:63]
	ds_read_b64_tr_b16 v[132:133], v14 offset:0x400
	ds_read_b64_tr_b16 v[134:135], v14 offset:0xc00
	v_mfma_f32_32x32x16_bf16 v[48:63], v[2:5], v[136:139], v[48:63]
	ds_read_b64_tr_b16 v[136:137], v14 offset:0x1400
	ds_read_b64_tr_b16 v[138:139], v14 offset:0x1c00
	v_mfma_f32_32x32x16_bf16 v[48:63], v[128:131], v[140:143], v[48:63]
	ds_read_b64_tr_b16 v[140:141], v14 offset:0x2400
	ds_read_b64_tr_b16 v[142:143], v14 offset:0x2c00
	v_mfma_f32_32x32x16_bf16 v[48:63], v[10:13], v[176:179], v[48:63]
	ds_read_b64_tr_b16 v[176:177], v14 offset:0x3400
	ds_read_b64_tr_b16 v[178:179], v14 offset:0x3c00
	s_waitcnt lgkmcnt(0)
	s_and_b64 vcc, exec, s[0:1]
	s_cbranch_vccnz .Lmy_slowd8_3
	s_cmpk_gt_u32 s17, 0xfb
	s_cbranch_scc1 .Lmy_slowd8_3
	s_mov_b64 s[14:15], -1
	s_add_i32 m0, s81, s26
	s_addk_i32 s31, 0xc000
	s_cmp_gt_i32 s18, 0
	s_cselect_b32 s14, s31, 0xc000
	s_waitcnt vmcnt(3) lgkmcnt(0)
	s_barrier
	v_mfma_f32_32x32x16_bf16 v[32:47], v[6:9], v[132:135], v[32:47]
	ds_read_b64_tr_b16 v[132:133], v14 offset:0x600
	ds_read_b64_tr_b16 v[134:135], v14 offset:0xe00
	v_mfma_f32_32x32x16_bf16 v[32:47], v[2:5], v[136:139], v[32:47]
	ds_read_b64_tr_b16 v[136:137], v14 offset:0x1600
	ds_read_b64_tr_b16 v[138:139], v14 offset:0x1e00
	v_mfma_f32_32x32x16_bf16 v[32:47], v[128:131], v[140:143], v[32:47]
	ds_read_b64_tr_b16 v[140:141], v14 offset:0x2600
	ds_read_b64_tr_b16 v[142:143], v14 offset:0x2e00
	v_mfma_f32_32x32x16_bf16 v[32:47], v[10:13], v[176:179], v[32:47]
	ds_read_b64_tr_b16 v[176:177], v14 offset:0x3600
	ds_read_b64_tr_b16 v[178:179], v14 offset:0x3e00
	s_waitcnt lgkmcnt(0)
	v_mfma_f32_32x32x16_bf16 v[16:31], v[6:9], v[132:135], v[16:31]
	s_and_b64 vcc, exec, s[0:1]
	v_mfma_f32_32x32x16_bf16 v[16:31], v[2:5], v[136:139], v[16:31]
	v_mfma_f32_32x32x16_bf16 v[16:31], v[128:131], v[140:143], v[16:31]
	v_mfma_f32_32x32x16_bf16 v[16:31], v[10:13], v[176:179], v[16:31]
	s_add_i32 s14, s63, s14
	global_load_lds_dwordx4 v[184:185], off
	s_mov_b32 m0, s14
	v_lshl_add_u64 v[184:185], v[184:185], 0, s[74:75]
	global_load_lds_dwordx4 v[186:187], off
	s_add_i32 m0, s14, 0x2000
	v_lshl_add_u64 v[2:3], v[186:187], 0, s[74:75]
	global_load_lds_dwordx4 v[188:189], off
	v_lshl_add_u64 v[4:5], v[188:189], 0, s[74:75]
	v_mov_b64_e32 v[188:189], v[4:5]
	v_mov_b64_e32 v[186:187], v[2:3]
	s_branch .LBB0_799
.Lmy_slowd8_3:
	v_mfma_f32_32x32x16_bf16 v[32:47], v[6:9], v[132:135], v[32:47]
	ds_read_b64_tr_b16 v[132:133], v14 offset:0x600
	ds_read_b64_tr_b16 v[134:135], v14 offset:0xe00
	v_mfma_f32_32x32x16_bf16 v[32:47], v[2:5], v[136:139], v[32:47]
	ds_read_b64_tr_b16 v[136:137], v14 offset:0x1600
	ds_read_b64_tr_b16 v[138:139], v14 offset:0x1e00
	v_mfma_f32_32x32x16_bf16 v[32:47], v[128:131], v[140:143], v[32:47]
	ds_read_b64_tr_b16 v[140:141], v14 offset:0x2600
	ds_read_b64_tr_b16 v[142:143], v14 offset:0x2e00
	v_mfma_f32_32x32x16_bf16 v[32:47], v[10:13], v[176:179], v[32:47]
	ds_read_b64_tr_b16 v[176:177], v14 offset:0x3600
	ds_read_b64_tr_b16 v[178:179], v14 offset:0x3e00
	s_waitcnt lgkmcnt(0)
	v_mfma_f32_32x32x16_bf16 v[16:31], v[6:9], v[132:135], v[16:31]
	s_and_b64 vcc, exec, s[0:1]
	v_mfma_f32_32x32x16_bf16 v[16:31], v[2:5], v[136:139], v[16:31]
	v_mfma_f32_32x32x16_bf16 v[16:31], v[128:131], v[140:143], v[16:31]
	v_mfma_f32_32x32x16_bf16 v[16:31], v[10:13], v[176:179], v[16:31]
	s_cbranch_vccnz .LBB0_799
